# deferred weight transposition: P0 converts layer 0 only; layer l+1 is converted inside PD of layer l, half the workgroups before and half after their attention work (staggered HBM streaming beside com
# speedup vs baseline: 1.0019x; 1.0016x over previous
.Lp0_tr_go:
	s_cmp_gt_i32 s29, 0x35ff
	v_lshlrev_b32_e32 v13, 3, v46
	s_cbranch_scc1 .LBB0_58
	s_lshl_b32 s30, s28, 3
	s_load_dwordx2 s[2:3], s[24:25], 0x68
	s_load_dwordx2 s[4:5], s[24:25], 0xd0
	s_load_dwordx2 s[6:7], s[24:25], 0xc0
	s_load_dwordx2 s[8:9], s[24:25], 0xe8
	v_lshrrev_b32_e32 v0, 3, v46
	v_and_b32_e32 v1, 7, v46
	v_lshlrev_b32_e32 v2, 4, v1
	v_lshlrev_b32_e32 v3, 3, v0
	v_lshlrev_b32_e32 v4, 2, v1
	v_lshlrev_b32_e32 v5, 4, v0
	s_waitcnt lgkmcnt(0)
	s_mov_b32 s11, s29
	s_cmp_ge_u32 s11, 0x6c00
	s_cselect_b32 s16, 0x6c00, 0
	s_cselect_b32 s10, 2, 0
	s_sub_u32 s11, s11, s16
	s_cmp_ge_u32 s11, 0x3600
	s_cselect_b32 s16, 0x3600, 0
	s_cselect_b32 s17, 1, 0
	s_sub_u32 s11, s11, s16
	s_add_u32 s10, s10, s17
	s_cmp_lt_u32 s11, 0x2400
	s_cbranch_scc1 .Ltr_in1
	s_cmp_lt_u32 s11, 0x3400
	s_cbranch_scc1 .Ltr_out1
	s_sub_u32 s11, s11, 0x3400
	s_and_b32 s16, s11, 15
	s_lshr_b32 s17, s11, 4
	s_movk_i32 s14, 0x2000
	s_movk_i32 s15, 0x800
	s_mov_b32 s34, 0x10000
	s_lshl_b32 s31, s10, 23
	s_lshl_b32 s11, s16, 19
	s_add_u32 s31, s31, s11
	s_lshl_b32 s11, s17, 8
	s_add_u32 s31, s31, s11
	s_add_u32 s31, s6, s31
	s_addc_u32 s11, s7, 0
	s_bfe_u32 s14, s17, 0x30001
	s_lshl_b32 s14, s14, 8
	s_lshr_b32 s15, s17, 4
	s_lshl_b32 s15, s15, 7
	s_add_u32 s14, s14, s15
	s_and_b32 s15, s17, 1
	s_lshl_b32 s15, s15, 6
	s_add_u32 s14, s14, s15
	s_lshl_b32 s14, s14, 11
	s_lshl_b32 s15, s16, 7
	s_add_u32 s14, s14, s15
	s_lshl_b32 s15, s10, 22
	s_add_u32 s14, s14, s15
	s_add_u32 s17, s14, 0xae00000
	s_mov_b32 s16, s31
	s_mov_b32 s31, s17
	s_mov_b32 s17, s11
	s_movk_i32 s14, 0x2000
	s_movk_i32 s15, 0x800
	s_branch .Ltr_dec1

.Ltr_loop:
	s_add_u32 s29, s29, s30
	s_cmp_gt_u32 s29, 0x35ff
	s_cbranch_scc1 .Ltr_lastA
	s_mov_b32 s11, s29
	s_cmp_ge_u32 s11, 0x6c00
	s_cselect_b32 s16, 0x6c00, 0
	s_cselect_b32 s10, 2, 0
	s_sub_u32 s11, s11, s16
	s_cmp_ge_u32 s11, 0x3600
	s_cselect_b32 s16, 0x3600, 0
	s_cselect_b32 s17, 1, 0
	s_sub_u32 s11, s11, s16
	s_add_u32 s10, s10, s17
	s_cmp_lt_u32 s11, 0x2400
	s_cbranch_scc1 .Ltr_in2
	s_cmp_lt_u32 s11, 0x3400
	s_cbranch_scc1 .Ltr_out2
	s_sub_u32 s11, s11, 0x3400
	s_and_b32 s16, s11, 15
	s_lshr_b32 s17, s11, 4
	s_movk_i32 s14, 0x2000
	s_movk_i32 s15, 0x800
	s_mov_b32 s35, 0x10000
	s_lshl_b32 s31, s10, 23
	s_lshl_b32 s11, s16, 19
	s_add_u32 s31, s31, s11
	s_lshl_b32 s11, s17, 8
	s_add_u32 s31, s31, s11
	s_add_u32 s31, s6, s31
	s_addc_u32 s11, s7, 0
	s_bfe_u32 s14, s17, 0x30001
	s_lshl_b32 s14, s14, 8
	s_lshr_b32 s15, s17, 4
	s_lshl_b32 s15, s15, 7
	s_add_u32 s14, s14, s15
	s_and_b32 s15, s17, 1
	s_lshl_b32 s15, s15, 6
	s_add_u32 s14, s14, s15
	s_lshl_b32 s14, s14, 11
	s_lshl_b32 s15, s16, 7
	s_add_u32 s14, s14, s15
	s_lshl_b32 s15, s10, 22
	s_add_u32 s14, s14, s15
	s_add_u32 s17, s14, 0xae00000
	s_mov_b32 s16, s31
	s_mov_b32 s31, s17
	s_mov_b32 s17, s11
	s_movk_i32 s14, 0x2000
	s_movk_i32 s15, 0x800
	s_branch .Ltr_dec2

.Ltr_dec2:
	s_add_u32 s40, s8, s31
	s_addc_u32 s41, s9, 0
	v_mad_u32_u24 v16, v3, s14, v2
	v_add_u32_e32 v17, s14, v16
	v_add_u32_e32 v18, s14, v17
	v_add_u32_e32 v19, s14, v18
	v_add_u32_e32 v20, s14, v19
	v_add_u32_e32 v21, s14, v20
	v_add_u32_e32 v22, s14, v21
	v_add_u32_e32 v23, s14, v22
	v_mad_u32_u24 v28, v4, s15, v5
	v_add_u32_e32 v29, s15, v28
	v_add_u32_e32 v30, s15, v29
	v_add_u32_e32 v31, s15, v30
	global_load_dwordx4 v[128:131], v16, s[16:17] nt
	global_load_dwordx4 v[132:135], v17, s[16:17] nt
	global_load_dwordx4 v[136:139], v18, s[16:17] nt
	global_load_dwordx4 v[140:143], v19, s[16:17] nt
	global_load_dwordx4 v[144:147], v20, s[16:17] nt
	global_load_dwordx4 v[148:151], v21, s[16:17] nt
	global_load_dwordx4 v[152:155], v22, s[16:17] nt
	global_load_dwordx4 v[156:159], v23, s[16:17] nt
	global_load_dwordx4 v[160:163], v16, s[16:17] offset:128 nt
	global_load_dwordx4 v[164:167], v17, s[16:17] offset:128 nt
	global_load_dwordx4 v[168:171], v18, s[16:17] offset:128 nt
	global_load_dwordx4 v[172:175], v19, s[16:17] offset:128 nt
	global_load_dwordx4 v[176:179], v20, s[16:17] offset:128 nt
	global_load_dwordx4 v[180:183], v21, s[16:17] offset:128 nt
	global_load_dwordx4 v[184:187], v22, s[16:17] offset:128 nt
	global_load_dwordx4 v[188:191], v23, s[16:17] offset:128 nt
	s_waitcnt vmcnt(16)
	v_cvt_pk_bf16_f32 v192, v64, v68
	v_cvt_pk_bf16_f32 v193, v72, v76
	v_cvt_pk_bf16_f32 v194, v80, v84
	v_cvt_pk_bf16_f32 v195, v88, v92
	v_cvt_pk_bf16_f32 v196, v65, v69
	v_cvt_pk_bf16_f32 v197, v73, v77
	v_cvt_pk_bf16_f32 v198, v81, v85
	v_cvt_pk_bf16_f32 v199, v89, v93
	v_cvt_pk_bf16_f32 v200, v66, v70
	v_cvt_pk_bf16_f32 v201, v74, v78
	v_cvt_pk_bf16_f32 v202, v82, v86
	v_cvt_pk_bf16_f32 v203, v90, v94
	v_cvt_pk_bf16_f32 v204, v67, v71
	v_cvt_pk_bf16_f32 v205, v75, v79
	v_cvt_pk_bf16_f32 v206, v83, v87
	v_cvt_pk_bf16_f32 v207, v91, v95
	global_store_dwordx4 v24, v[192:195], s[18:19] nt
	global_store_dwordx4 v25, v[196:199], s[18:19] nt
	global_store_dwordx4 v26, v[200:203], s[18:19] nt
	global_store_dwordx4 v27, v[204:207], s[18:19] nt
	v_cvt_pk_bf16_f32 v48, v96, v100
	v_cvt_pk_bf16_f32 v49, v104, v108
	v_cvt_pk_bf16_f32 v50, v112, v116
	v_cvt_pk_bf16_f32 v51, v120, v124
	v_cvt_pk_bf16_f32 v52, v97, v101
	v_cvt_pk_bf16_f32 v53, v105, v109
	v_cvt_pk_bf16_f32 v54, v113, v117
	v_cvt_pk_bf16_f32 v55, v121, v125
	v_cvt_pk_bf16_f32 v56, v98, v102
	v_cvt_pk_bf16_f32 v57, v106, v110
	v_cvt_pk_bf16_f32 v58, v114, v118
	v_cvt_pk_bf16_f32 v59, v122, v126
	v_cvt_pk_bf16_f32 v60, v99, v103
	v_cvt_pk_bf16_f32 v61, v107, v111
	v_cvt_pk_bf16_f32 v62, v115, v119
	v_cvt_pk_bf16_f32 v63, v123, v127
	s_add_u32 s10, s18, s34
	s_addc_u32 s11, s19, 0
	global_store_dwordx4 v24, v[48:51], s[10:11] nt
	global_store_dwordx4 v25, v[52:55], s[10:11] nt
	global_store_dwordx4 v26, v[56:59], s[10:11] nt
	global_store_dwordx4 v27, v[60:63], s[10:11] nt
	s_add_u32 s29, s29, s30
	s_cmp_gt_u32 s29, 0x35ff
	s_cbranch_scc1 .Ltr_lastB
	s_mov_b32 s11, s29
	s_cmp_ge_u32 s11, 0x6c00
	s_cselect_b32 s16, 0x6c00, 0
	s_cselect_b32 s10, 2, 0
	s_sub_u32 s11, s11, s16
	s_cmp_ge_u32 s11, 0x3600
	s_cselect_b32 s16, 0x3600, 0
	s_cselect_b32 s17, 1, 0
	s_sub_u32 s11, s11, s16
	s_add_u32 s10, s10, s17
	s_cmp_lt_u32 s11, 0x2400
	s_cbranch_scc1 .Ltr_in3
	s_cmp_lt_u32 s11, 0x3400
	s_cbranch_scc1 .Ltr_out3
	s_sub_u32 s11, s11, 0x3400
	s_and_b32 s16, s11, 15
	s_lshr_b32 s17, s11, 4
	s_movk_i32 s14, 0x2000
	s_movk_i32 s15, 0x800
	s_mov_b32 s34, 0x10000
	s_lshl_b32 s31, s10, 23
	s_lshl_b32 s11, s16, 19
	s_add_u32 s31, s31, s11
	s_lshl_b32 s11, s17, 8
	s_add_u32 s31, s31, s11
	s_add_u32 s31, s6, s31
	s_addc_u32 s11, s7, 0
	s_bfe_u32 s14, s17, 0x30001
	s_lshl_b32 s14, s14, 8
	s_lshr_b32 s15, s17, 4
	s_lshl_b32 s15, s15, 7
	s_add_u32 s14, s14, s15
	s_and_b32 s15, s17, 1
	s_lshl_b32 s15, s15, 6
	s_add_u32 s14, s14, s15
	s_lshl_b32 s14, s14, 11
	s_lshl_b32 s15, s16, 7
	s_add_u32 s14, s14, s15
	s_lshl_b32 s15, s10, 22
	s_add_u32 s14, s14, s15
	s_add_u32 s17, s14, 0xae00000
	s_mov_b32 s16, s31
	s_mov_b32 s31, s17
	s_mov_b32 s17, s11
	s_movk_i32 s14, 0x2000
	s_movk_i32 s15, 0x800
	s_branch .Ltr_dec3

.LBB0_638:
	v_readlane_b32 s4, v255, 2
	v_readlane_b32 s6, v255, 4
	v_readlane_b32 s5, v255, 3
	s_cmp_gt_i32 s6, s56
	s_mul_i32 s6, s92, 6
	v_readlane_b32 s7, v255, 5
	s_cselect_b64 s[2:3], -1, 0
	s_xor_b64 s[4:5], s[18:19], -1
	s_add_i32 s37, s6, 5
	s_cmp_lt_i32 s37, s7
	s_cselect_b64 s[96:97], -1, 0
	s_or_b64 s[2:3], s[2:3], s[4:5]
	s_and_b64 vcc, exec, s[2:3]
	s_cbranch_vccnz .LBB0_823
	s_cmp_ge_u32 s92, 3
	s_cbranch_scc1 .Ltq1_exit
	s_bitcmp1_b32 s12, 3
	s_cbranch_scc1 .Ltq1_exit
	v_and_b32_e32 v46, 63, v220
	v_readfirstlane_b32 s2, v220
	s_ashr_i32 s43, s2, 6
	s_lshl_b32 s2, s12, 3
	s_add_i32 s29, s43, s2
	s_add_u32 s48, s92, 1
	s_mul_i32 s48, s48, 0x3600
	s_add_u32 s29, s29, s48
	s_add_u32 s44, s48, 0x35ff
	s_cmp_gt_u32 s29, s44
	s_cbranch_scc1 .Ltq1_exit
	s_lshl_b32 s30, s13, 3
	s_load_dwordx2 s[2:3], s[0:1], 0x68
	s_load_dwordx2 s[4:5], s[0:1], 0xd0
	s_load_dwordx2 s[6:7], s[0:1], 0xc0
	s_load_dwordx2 s[38:39], s[0:1], 0xe8
	v_lshrrev_b32_e32 v0, 3, v46
	v_and_b32_e32 v1, 7, v46
	v_lshlrev_b32_e32 v2, 4, v1
	v_lshlrev_b32_e32 v3, 3, v0
	v_lshlrev_b32_e32 v4, 2, v1
	v_lshlrev_b32_e32 v5, 4, v0
	s_waitcnt lgkmcnt(0)
	s_mov_b32 s11, s29
	s_cmp_ge_u32 s11, 0x6c00
	s_cselect_b32 s80, 0x6c00, 0
	s_cselect_b32 s10, 2, 0
	s_sub_u32 s11, s11, s80
	s_cmp_ge_u32 s11, 0x3600
	s_cselect_b32 s80, 0x3600, 0
	s_cselect_b32 s81, 1, 0
	s_sub_u32 s11, s11, s80
	s_add_u32 s10, s10, s81
	s_cmp_lt_u32 s11, 0x2400
	s_cbranch_scc1 .Ltq1_in1
	s_cmp_lt_u32 s11, 0x3400
	s_cbranch_scc1 .Ltq1_out1
	s_sub_u32 s11, s11, 0x3400
	s_and_b32 s80, s11, 15
	s_lshr_b32 s81, s11, 4
	s_movk_i32 s78, 0x2000
	s_movk_i32 s79, 0x800
	s_mov_b32 s34, 0x10000
	s_lshl_b32 s31, s10, 23
	s_lshl_b32 s11, s80, 19
	s_add_u32 s31, s31, s11
	s_lshl_b32 s11, s81, 8
	s_add_u32 s31, s31, s11
	s_add_u32 s31, s6, s31
	s_addc_u32 s11, s7, 0
	s_bfe_u32 s78, s81, 0x30001
	s_lshl_b32 s78, s78, 8
	s_lshr_b32 s79, s81, 4
	s_lshl_b32 s79, s79, 7
	s_add_u32 s78, s78, s79
	s_and_b32 s79, s81, 1
	s_lshl_b32 s79, s79, 6
	s_add_u32 s78, s78, s79
	s_lshl_b32 s78, s78, 11
	s_lshl_b32 s79, s80, 7
	s_add_u32 s78, s78, s79
	s_lshl_b32 s79, s10, 22
	s_add_u32 s78, s78, s79
	s_add_u32 s81, s78, 0xae00000
	s_mov_b32 s80, s31
	s_mov_b32 s31, s81
	s_mov_b32 s81, s11
	s_movk_i32 s78, 0x2000
	s_movk_i32 s79, 0x800
	s_branch .Ltq1_dec1
.Ltq1_in1:
	s_and_b32 s80, s11, 63
	s_lshr_b32 s81, s11, 6
	s_mov_b32 s34, 0x40000
	s_mul_i32 s31, s10, 0x9000000
	s_mul_i32 s11, s80, 0x240000
	s_add_u32 s31, s31, s11
	s_lshl_b32 s11, s81, 8
	s_add_u32 s31, s31, s11
	s_add_u32 s78, s2, s31
	s_addc_u32 s79, s3, 0
	s_mul_i32 s31, s10, 0x4800000
	s_lshl_b32 s11, s81, 19
	s_add_u32 s31, s31, s11
	s_lshl_b32 s11, s80, 7
	s_add_u32 s31, s31, s11
	s_add_u32 s31, s31, 0x14600000
	s_mov_b32 s80, s78
	s_mov_b32 s81, s79
	s_mov_b32 s78, 0x9000
	s_movk_i32 s79, 0x2000
	s_branch .Ltq1_dec1
.Ltq1_out1:
	s_sub_u32 s11, s11, 0x2400
	s_and_b32 s80, s11, 63
	s_lshr_b32 s81, s11, 6
	s_mov_b32 s34, 0x40000
	s_lshl_b32 s31, s10, 26
	s_lshl_b32 s11, s80, 20
	s_add_u32 s31, s31, s11
	s_lshl_b32 s11, s81, 8
	s_add_u32 s31, s31, s11
	s_add_u32 s78, s4, s31
	s_addc_u32 s79, s5, 0
	s_lshl_b32 s31, s10, 25
	s_lshl_b32 s11, s81, 19
	s_add_u32 s31, s31, s11
	s_lshl_b32 s11, s80, 7
	s_add_u32 s31, s31, s11
	s_add_u32 s31, s31, 0xc600000
	s_mov_b32 s80, s78
	s_mov_b32 s81, s79
	s_movk_i32 s78, 0x4000
	s_movk_i32 s79, 0x2000
.Ltq1_dec1:
	s_add_u32 s90, s38, s31
	s_addc_u32 s91, s39, 0
	v_mad_u32_u24 v16, v3, s78, v2
	v_add_u32_e32 v17, s78, v16
	v_add_u32_e32 v18, s78, v17
	v_add_u32_e32 v19, s78, v18
	v_add_u32_e32 v20, s78, v19
	v_add_u32_e32 v21, s78, v20
	v_add_u32_e32 v22, s78, v21
	v_add_u32_e32 v23, s78, v22
	v_mad_u32_u24 v24, v4, s79, v5
	v_add_u32_e32 v25, s79, v24
	v_add_u32_e32 v26, s79, v25
	v_add_u32_e32 v27, s79, v26
	global_load_dwordx4 v[64:67], v16, s[80:81] nt
	global_load_dwordx4 v[68:71], v17, s[80:81] nt
	global_load_dwordx4 v[72:75], v18, s[80:81] nt
	global_load_dwordx4 v[76:79], v19, s[80:81] nt
	global_load_dwordx4 v[80:83], v20, s[80:81] nt
	global_load_dwordx4 v[84:87], v21, s[80:81] nt
	global_load_dwordx4 v[88:91], v22, s[80:81] nt
	global_load_dwordx4 v[92:95], v23, s[80:81] nt
	global_load_dwordx4 v[96:99], v16, s[80:81] offset:128 nt
	global_load_dwordx4 v[100:103], v17, s[80:81] offset:128 nt
	global_load_dwordx4 v[104:107], v18, s[80:81] offset:128 nt
	global_load_dwordx4 v[108:111], v19, s[80:81] offset:128 nt
	global_load_dwordx4 v[112:115], v20, s[80:81] offset:128 nt
	global_load_dwordx4 v[116:119], v21, s[80:81] offset:128 nt
	global_load_dwordx4 v[120:123], v22, s[80:81] offset:128 nt
	global_load_dwordx4 v[124:127], v23, s[80:81] offset:128 nt
.Ltq1_loop:
	s_add_u32 s29, s29, s30
	s_cmp_gt_u32 s29, s44
	s_cbranch_scc1 .Ltq1_lastA
	s_mov_b32 s11, s29
	s_cmp_ge_u32 s11, 0x6c00
	s_cselect_b32 s80, 0x6c00, 0
	s_cselect_b32 s10, 2, 0
	s_sub_u32 s11, s11, s80
	s_cmp_ge_u32 s11, 0x3600
	s_cselect_b32 s80, 0x3600, 0
	s_cselect_b32 s81, 1, 0
	s_sub_u32 s11, s11, s80
	s_add_u32 s10, s10, s81
	s_cmp_lt_u32 s11, 0x2400
	s_cbranch_scc1 .Ltq1_in2
	s_cmp_lt_u32 s11, 0x3400
	s_cbranch_scc1 .Ltq1_out2
	s_sub_u32 s11, s11, 0x3400
	s_and_b32 s80, s11, 15
	s_lshr_b32 s81, s11, 4
	s_movk_i32 s78, 0x2000
	s_movk_i32 s79, 0x800
	s_mov_b32 s35, 0x10000
	s_lshl_b32 s31, s10, 23
	s_lshl_b32 s11, s80, 19
	s_add_u32 s31, s31, s11
	s_lshl_b32 s11, s81, 8
	s_add_u32 s31, s31, s11
	s_add_u32 s31, s6, s31
	s_addc_u32 s11, s7, 0
	s_bfe_u32 s78, s81, 0x30001
	s_lshl_b32 s78, s78, 8
	s_lshr_b32 s79, s81, 4
	s_lshl_b32 s79, s79, 7
	s_add_u32 s78, s78, s79
	s_and_b32 s79, s81, 1
	s_lshl_b32 s79, s79, 6
	s_add_u32 s78, s78, s79
	s_lshl_b32 s78, s78, 11
	s_lshl_b32 s79, s80, 7
	s_add_u32 s78, s78, s79
	s_lshl_b32 s79, s10, 22
	s_add_u32 s78, s78, s79
	s_add_u32 s81, s78, 0xae00000
	s_mov_b32 s80, s31
	s_mov_b32 s31, s81
	s_mov_b32 s81, s11
	s_movk_i32 s78, 0x2000
	s_movk_i32 s79, 0x800
	s_branch .Ltq1_dec2
.Ltq1_in2:
	s_and_b32 s80, s11, 63
	s_lshr_b32 s81, s11, 6
	s_mov_b32 s35, 0x40000
	s_mul_i32 s31, s10, 0x9000000
	s_mul_i32 s11, s80, 0x240000
	s_add_u32 s31, s31, s11
	s_lshl_b32 s11, s81, 8
	s_add_u32 s31, s31, s11
	s_add_u32 s78, s2, s31
	s_addc_u32 s79, s3, 0
	s_mul_i32 s31, s10, 0x4800000
	s_lshl_b32 s11, s81, 19
	s_add_u32 s31, s31, s11
	s_lshl_b32 s11, s80, 7
	s_add_u32 s31, s31, s11
	s_add_u32 s31, s31, 0x14600000
	s_mov_b32 s80, s78
	s_mov_b32 s81, s79
	s_mov_b32 s78, 0x9000
	s_movk_i32 s79, 0x2000
	s_branch .Ltq1_dec2
.Ltq1_out2:
	s_sub_u32 s11, s11, 0x2400
	s_and_b32 s80, s11, 63
	s_lshr_b32 s81, s11, 6
	s_mov_b32 s35, 0x40000
	s_lshl_b32 s31, s10, 26
	s_lshl_b32 s11, s80, 20
	s_add_u32 s31, s31, s11
	s_lshl_b32 s11, s81, 8
	s_add_u32 s31, s31, s11
	s_add_u32 s78, s4, s31
	s_addc_u32 s79, s5, 0
	s_lshl_b32 s31, s10, 25
	s_lshl_b32 s11, s81, 19
	s_add_u32 s31, s31, s11
	s_lshl_b32 s11, s80, 7
	s_add_u32 s31, s31, s11
	s_add_u32 s31, s31, 0xc600000
	s_mov_b32 s80, s78
	s_mov_b32 s81, s79
	s_movk_i32 s78, 0x4000
	s_movk_i32 s79, 0x2000
.Ltq1_dec2:
	s_add_u32 s98, s38, s31
	s_addc_u32 s99, s39, 0
	v_mad_u32_u24 v16, v3, s78, v2
	v_add_u32_e32 v17, s78, v16
	v_add_u32_e32 v18, s78, v17
	v_add_u32_e32 v19, s78, v18
	v_add_u32_e32 v20, s78, v19
	v_add_u32_e32 v21, s78, v20
	v_add_u32_e32 v22, s78, v21
	v_add_u32_e32 v23, s78, v22
	v_mad_u32_u24 v28, v4, s79, v5
	v_add_u32_e32 v29, s79, v28
	v_add_u32_e32 v30, s79, v29
	v_add_u32_e32 v31, s79, v30
	global_load_dwordx4 v[128:131], v16, s[80:81] nt
	global_load_dwordx4 v[132:135], v17, s[80:81] nt
	global_load_dwordx4 v[136:139], v18, s[80:81] nt
	global_load_dwordx4 v[140:143], v19, s[80:81] nt
	global_load_dwordx4 v[144:147], v20, s[80:81] nt
	global_load_dwordx4 v[148:151], v21, s[80:81] nt
	global_load_dwordx4 v[152:155], v22, s[80:81] nt
	global_load_dwordx4 v[156:159], v23, s[80:81] nt
	global_load_dwordx4 v[160:163], v16, s[80:81] offset:128 nt
	global_load_dwordx4 v[164:167], v17, s[80:81] offset:128 nt
	global_load_dwordx4 v[168:171], v18, s[80:81] offset:128 nt
	global_load_dwordx4 v[172:175], v19, s[80:81] offset:128 nt
	global_load_dwordx4 v[176:179], v20, s[80:81] offset:128 nt
	global_load_dwordx4 v[180:183], v21, s[80:81] offset:128 nt
	global_load_dwordx4 v[184:187], v22, s[80:81] offset:128 nt
	global_load_dwordx4 v[188:191], v23, s[80:81] offset:128 nt
	s_waitcnt vmcnt(16)
	v_cvt_pk_bf16_f32 v192, v64, v68
	v_cvt_pk_bf16_f32 v193, v72, v76
	v_cvt_pk_bf16_f32 v194, v80, v84
	v_cvt_pk_bf16_f32 v195, v88, v92
	v_cvt_pk_bf16_f32 v196, v65, v69
	v_cvt_pk_bf16_f32 v197, v73, v77
	v_cvt_pk_bf16_f32 v198, v81, v85
	v_cvt_pk_bf16_f32 v199, v89, v93
	v_cvt_pk_bf16_f32 v200, v66, v70
	v_cvt_pk_bf16_f32 v201, v74, v78
	v_cvt_pk_bf16_f32 v202, v82, v86
	v_cvt_pk_bf16_f32 v203, v90, v94
	v_cvt_pk_bf16_f32 v204, v67, v71
	v_cvt_pk_bf16_f32 v205, v75, v79
	v_cvt_pk_bf16_f32 v206, v83, v87
	v_cvt_pk_bf16_f32 v207, v91, v95
	global_store_dwordx4 v24, v[192:195], s[90:91] nt
	global_store_dwordx4 v25, v[196:199], s[90:91] nt
	global_store_dwordx4 v26, v[200:203], s[90:91] nt
	global_store_dwordx4 v27, v[204:207], s[90:91] nt
	v_cvt_pk_bf16_f32 v48, v96, v100
	v_cvt_pk_bf16_f32 v49, v104, v108
	v_cvt_pk_bf16_f32 v50, v112, v116
	v_cvt_pk_bf16_f32 v51, v120, v124
	v_cvt_pk_bf16_f32 v52, v97, v101
	v_cvt_pk_bf16_f32 v53, v105, v109
	v_cvt_pk_bf16_f32 v54, v113, v117
	v_cvt_pk_bf16_f32 v55, v121, v125
	v_cvt_pk_bf16_f32 v56, v98, v102
	v_cvt_pk_bf16_f32 v57, v106, v110
	v_cvt_pk_bf16_f32 v58, v114, v118
	v_cvt_pk_bf16_f32 v59, v122, v126
	v_cvt_pk_bf16_f32 v60, v99, v103
	v_cvt_pk_bf16_f32 v61, v107, v111
	v_cvt_pk_bf16_f32 v62, v115, v119
	v_cvt_pk_bf16_f32 v63, v123, v127
	s_add_u32 s10, s90, s34
	s_addc_u32 s11, s91, 0
	global_store_dwordx4 v24, v[48:51], s[10:11] nt
	global_store_dwordx4 v25, v[52:55], s[10:11] nt
	global_store_dwordx4 v26, v[56:59], s[10:11] nt
	global_store_dwordx4 v27, v[60:63], s[10:11] nt
	s_add_u32 s29, s29, s30
	s_cmp_gt_u32 s29, s44
	s_cbranch_scc1 .Ltq1_lastB
	s_mov_b32 s11, s29
	s_cmp_ge_u32 s11, 0x6c00
	s_cselect_b32 s80, 0x6c00, 0
	s_cselect_b32 s10, 2, 0
	s_sub_u32 s11, s11, s80
	s_cmp_ge_u32 s11, 0x3600
	s_cselect_b32 s80, 0x3600, 0
	s_cselect_b32 s81, 1, 0
	s_sub_u32 s11, s11, s80
	s_add_u32 s10, s10, s81
	s_cmp_lt_u32 s11, 0x2400
	s_cbranch_scc1 .Ltq1_in3
	s_cmp_lt_u32 s11, 0x3400
	s_cbranch_scc1 .Ltq1_out3
	s_sub_u32 s11, s11, 0x3400
	s_and_b32 s80, s11, 15
	s_lshr_b32 s81, s11, 4
	s_movk_i32 s78, 0x2000
	s_movk_i32 s79, 0x800
	s_mov_b32 s34, 0x10000
	s_lshl_b32 s31, s10, 23
	s_lshl_b32 s11, s80, 19
	s_add_u32 s31, s31, s11
	s_lshl_b32 s11, s81, 8
	s_add_u32 s31, s31, s11
	s_add_u32 s31, s6, s31
	s_addc_u32 s11, s7, 0
	s_bfe_u32 s78, s81, 0x30001
	s_lshl_b32 s78, s78, 8
	s_lshr_b32 s79, s81, 4
	s_lshl_b32 s79, s79, 7
	s_add_u32 s78, s78, s79
	s_and_b32 s79, s81, 1
	s_lshl_b32 s79, s79, 6
	s_add_u32 s78, s78, s79
	s_lshl_b32 s78, s78, 11
	s_lshl_b32 s79, s80, 7
	s_add_u32 s78, s78, s79
	s_lshl_b32 s79, s10, 22
	s_add_u32 s78, s78, s79
	s_add_u32 s81, s78, 0xae00000
	s_mov_b32 s80, s31
	s_mov_b32 s31, s81
	s_mov_b32 s81, s11
	s_movk_i32 s78, 0x2000
	s_movk_i32 s79, 0x800
	s_branch .Ltq1_dec3

.Ltq1_dec3:
	s_add_u32 s90, s38, s31
	s_addc_u32 s91, s39, 0
	v_mad_u32_u24 v16, v3, s78, v2
	v_add_u32_e32 v17, s78, v16
	v_add_u32_e32 v18, s78, v17
	v_add_u32_e32 v19, s78, v18
	v_add_u32_e32 v20, s78, v19
	v_add_u32_e32 v21, s78, v20
	v_add_u32_e32 v22, s78, v21
	v_add_u32_e32 v23, s78, v22
	v_mad_u32_u24 v24, v4, s79, v5
	v_add_u32_e32 v25, s79, v24
	v_add_u32_e32 v26, s79, v25
	v_add_u32_e32 v27, s79, v26
	global_load_dwordx4 v[64:67], v16, s[80:81] nt
	global_load_dwordx4 v[68:71], v17, s[80:81] nt
	global_load_dwordx4 v[72:75], v18, s[80:81] nt
	global_load_dwordx4 v[76:79], v19, s[80:81] nt
	global_load_dwordx4 v[80:83], v20, s[80:81] nt
	global_load_dwordx4 v[84:87], v21, s[80:81] nt
	global_load_dwordx4 v[88:91], v22, s[80:81] nt
	global_load_dwordx4 v[92:95], v23, s[80:81] nt
	global_load_dwordx4 v[96:99], v16, s[80:81] offset:128 nt
	global_load_dwordx4 v[100:103], v17, s[80:81] offset:128 nt
	global_load_dwordx4 v[104:107], v18, s[80:81] offset:128 nt
	global_load_dwordx4 v[108:111], v19, s[80:81] offset:128 nt
	global_load_dwordx4 v[112:115], v20, s[80:81] offset:128 nt
	global_load_dwordx4 v[116:119], v21, s[80:81] offset:128 nt
	global_load_dwordx4 v[120:123], v22, s[80:81] offset:128 nt
	global_load_dwordx4 v[124:127], v23, s[80:81] offset:128 nt
	s_waitcnt vmcnt(16)
	v_cvt_pk_bf16_f32 v192, v128, v132
	v_cvt_pk_bf16_f32 v193, v136, v140
	v_cvt_pk_bf16_f32 v194, v144, v148
	v_cvt_pk_bf16_f32 v195, v152, v156
	v_cvt_pk_bf16_f32 v196, v129, v133
	v_cvt_pk_bf16_f32 v197, v137, v141
	v_cvt_pk_bf16_f32 v198, v145, v149
	v_cvt_pk_bf16_f32 v199, v153, v157
	v_cvt_pk_bf16_f32 v200, v130, v134
	v_cvt_pk_bf16_f32 v201, v138, v142
	v_cvt_pk_bf16_f32 v202, v146, v150
	v_cvt_pk_bf16_f32 v203, v154, v158
	v_cvt_pk_bf16_f32 v204, v131, v135
	v_cvt_pk_bf16_f32 v205, v139, v143
	v_cvt_pk_bf16_f32 v206, v147, v151
	v_cvt_pk_bf16_f32 v207, v155, v159
	global_store_dwordx4 v28, v[192:195], s[98:99] nt
	global_store_dwordx4 v29, v[196:199], s[98:99] nt
	global_store_dwordx4 v30, v[200:203], s[98:99] nt
	global_store_dwordx4 v31, v[204:207], s[98:99] nt
	v_cvt_pk_bf16_f32 v48, v160, v164
	v_cvt_pk_bf16_f32 v49, v168, v172
	v_cvt_pk_bf16_f32 v50, v176, v180
	v_cvt_pk_bf16_f32 v51, v184, v188
	v_cvt_pk_bf16_f32 v52, v161, v165
	v_cvt_pk_bf16_f32 v53, v169, v173
	v_cvt_pk_bf16_f32 v54, v177, v181
	v_cvt_pk_bf16_f32 v55, v185, v189
	v_cvt_pk_bf16_f32 v56, v162, v166
	v_cvt_pk_bf16_f32 v57, v170, v174
	v_cvt_pk_bf16_f32 v58, v178, v182
	v_cvt_pk_bf16_f32 v59, v186, v190
	v_cvt_pk_bf16_f32 v60, v163, v167
	v_cvt_pk_bf16_f32 v61, v171, v175
	v_cvt_pk_bf16_f32 v62, v179, v183
	v_cvt_pk_bf16_f32 v63, v187, v191
	s_add_u32 s10, s98, s35
	s_addc_u32 s11, s99, 0
	global_store_dwordx4 v28, v[48:51], s[10:11] nt
	global_store_dwordx4 v29, v[52:55], s[10:11] nt
	global_store_dwordx4 v30, v[56:59], s[10:11] nt
	global_store_dwordx4 v31, v[60:63], s[10:11] nt
	s_branch .Ltq1_loop
.Ltq1_lastA:
	s_waitcnt vmcnt(0)
	v_cvt_pk_bf16_f32 v192, v64, v68
	v_cvt_pk_bf16_f32 v193, v72, v76
	v_cvt_pk_bf16_f32 v194, v80, v84
	v_cvt_pk_bf16_f32 v195, v88, v92
	v_cvt_pk_bf16_f32 v196, v65, v69
	v_cvt_pk_bf16_f32 v197, v73, v77
	v_cvt_pk_bf16_f32 v198, v81, v85
	v_cvt_pk_bf16_f32 v199, v89, v93
	v_cvt_pk_bf16_f32 v200, v66, v70
	v_cvt_pk_bf16_f32 v201, v74, v78
	v_cvt_pk_bf16_f32 v202, v82, v86
	v_cvt_pk_bf16_f32 v203, v90, v94
	v_cvt_pk_bf16_f32 v204, v67, v71
	v_cvt_pk_bf16_f32 v205, v75, v79
	v_cvt_pk_bf16_f32 v206, v83, v87
	v_cvt_pk_bf16_f32 v207, v91, v95
	global_store_dwordx4 v24, v[192:195], s[90:91] nt
	global_store_dwordx4 v25, v[196:199], s[90:91] nt
	global_store_dwordx4 v26, v[200:203], s[90:91] nt
	global_store_dwordx4 v27, v[204:207], s[90:91] nt
	v_cvt_pk_bf16_f32 v48, v96, v100
	v_cvt_pk_bf16_f32 v49, v104, v108
	v_cvt_pk_bf16_f32 v50, v112, v116
	v_cvt_pk_bf16_f32 v51, v120, v124
	v_cvt_pk_bf16_f32 v52, v97, v101
	v_cvt_pk_bf16_f32 v53, v105, v109
	v_cvt_pk_bf16_f32 v54, v113, v117
	v_cvt_pk_bf16_f32 v55, v121, v125
	v_cvt_pk_bf16_f32 v56, v98, v102
	v_cvt_pk_bf16_f32 v57, v106, v110
	v_cvt_pk_bf16_f32 v58, v114, v118
	v_cvt_pk_bf16_f32 v59, v122, v126
	v_cvt_pk_bf16_f32 v60, v99, v103
	v_cvt_pk_bf16_f32 v61, v107, v111
	v_cvt_pk_bf16_f32 v62, v115, v119
	v_cvt_pk_bf16_f32 v63, v123, v127
	s_add_u32 s10, s90, s34
	s_addc_u32 s11, s91, 0
	global_store_dwordx4 v24, v[48:51], s[10:11] nt
	global_store_dwordx4 v25, v[52:55], s[10:11] nt
	global_store_dwordx4 v26, v[56:59], s[10:11] nt
	global_store_dwordx4 v27, v[60:63], s[10:11] nt
	s_branch .Ltq1_exit
.Ltq1_lastB:
	s_waitcnt vmcnt(0)
	v_cvt_pk_bf16_f32 v192, v128, v132
	v_cvt_pk_bf16_f32 v193, v136, v140
	v_cvt_pk_bf16_f32 v194, v144, v148
	v_cvt_pk_bf16_f32 v195, v152, v156
	v_cvt_pk_bf16_f32 v196, v129, v133
	v_cvt_pk_bf16_f32 v197, v137, v141
	v_cvt_pk_bf16_f32 v198, v145, v149
	v_cvt_pk_bf16_f32 v199, v153, v157
	v_cvt_pk_bf16_f32 v200, v130, v134
	v_cvt_pk_bf16_f32 v201, v138, v142
	v_cvt_pk_bf16_f32 v202, v146, v150
	v_cvt_pk_bf16_f32 v203, v154, v158
	v_cvt_pk_bf16_f32 v204, v131, v135
	v_cvt_pk_bf16_f32 v205, v139, v143
	v_cvt_pk_bf16_f32 v206, v147, v151
	v_cvt_pk_bf16_f32 v207, v155, v159
	global_store_dwordx4 v28, v[192:195], s[98:99] nt
	global_store_dwordx4 v29, v[196:199], s[98:99] nt
	global_store_dwordx4 v30, v[200:203], s[98:99] nt
	global_store_dwordx4 v31, v[204:207], s[98:99] nt
	v_cvt_pk_bf16_f32 v48, v160, v164
	v_cvt_pk_bf16_f32 v49, v168, v172
	v_cvt_pk_bf16_f32 v50, v176, v180
	v_cvt_pk_bf16_f32 v51, v184, v188
	v_cvt_pk_bf16_f32 v52, v161, v165
	v_cvt_pk_bf16_f32 v53, v169, v173
	v_cvt_pk_bf16_f32 v54, v177, v181
	v_cvt_pk_bf16_f32 v55, v185, v189
	v_cvt_pk_bf16_f32 v56, v162, v166
	v_cvt_pk_bf16_f32 v57, v170, v174
	v_cvt_pk_bf16_f32 v58, v178, v182
	v_cvt_pk_bf16_f32 v59, v186, v190
	v_cvt_pk_bf16_f32 v60, v163, v167
	v_cvt_pk_bf16_f32 v61, v171, v175
	v_cvt_pk_bf16_f32 v62, v179, v183
	v_cvt_pk_bf16_f32 v63, v187, v191
	s_add_u32 s10, s98, s35
	s_addc_u32 s11, s99, 0
	global_store_dwordx4 v28, v[48:51], s[10:11] nt
	global_store_dwordx4 v29, v[52:55], s[10:11] nt
	global_store_dwordx4 v30, v[56:59], s[10:11] nt
	global_store_dwordx4 v31, v[60:63], s[10:11] nt
.Ltq1_exit:
	s_waitcnt vmcnt(0)
	v_mov_b32_e32 v177, 0
	v_readlane_b32 s4, v255, 24
	v_readlane_b32 s5, v255, 25
	s_mov_b64 s[2:3], -1
	s_and_b64 vcc, exec, s[4:5]
	s_waitcnt vmcnt(0)
	s_cbranch_vccz .LBB0_658
	v_readlane_b32 s2, v255, 26
	v_readlane_b32 s3, v255, 27
	s_mov_b64 s[6:7], s[0:1]
	s_andn2_b64 vcc, exec, s[2:3]
	v_readlane_b32 s8, v255, 40
	v_readlane_b32 s9, v255, 28
	s_barrier
	s_cbranch_vccz .LBB0_644

.LBB0_774:
	s_cmp_ge_u32 s92, 3
	s_cbranch_scc1 .Ltq2_exit
	s_bitcmp1_b32 s12, 3
	s_cbranch_scc0 .Ltq2_exit
	v_and_b32_e32 v46, 63, v220
	v_readfirstlane_b32 s2, v220
	s_ashr_i32 s43, s2, 6
	s_lshl_b32 s2, s12, 3
	s_add_i32 s29, s43, s2
	s_add_u32 s48, s92, 1
	s_mul_i32 s48, s48, 0x3600
	s_add_u32 s29, s29, s48
	s_add_u32 s44, s48, 0x35ff
	s_cmp_gt_u32 s29, s44
	s_cbranch_scc1 .Ltq2_exit
	s_lshl_b32 s30, s13, 3
	s_load_dwordx2 s[2:3], s[0:1], 0x68
	s_load_dwordx2 s[4:5], s[0:1], 0xd0
	s_load_dwordx2 s[6:7], s[0:1], 0xc0
	s_load_dwordx2 s[38:39], s[0:1], 0xe8
	v_lshrrev_b32_e32 v0, 3, v46
	v_and_b32_e32 v1, 7, v46
	v_lshlrev_b32_e32 v2, 4, v1
	v_lshlrev_b32_e32 v3, 3, v0
	v_lshlrev_b32_e32 v4, 2, v1
	v_lshlrev_b32_e32 v5, 4, v0
	s_waitcnt lgkmcnt(0)
	s_mov_b32 s11, s29
	s_cmp_ge_u32 s11, 0x6c00
	s_cselect_b32 s80, 0x6c00, 0
	s_cselect_b32 s10, 2, 0
	s_sub_u32 s11, s11, s80
	s_cmp_ge_u32 s11, 0x3600
	s_cselect_b32 s80, 0x3600, 0
	s_cselect_b32 s81, 1, 0
	s_sub_u32 s11, s11, s80
	s_add_u32 s10, s10, s81
	s_cmp_lt_u32 s11, 0x2400
	s_cbranch_scc1 .Ltq2_in1
	s_cmp_lt_u32 s11, 0x3400
	s_cbranch_scc1 .Ltq2_out1
	s_sub_u32 s11, s11, 0x3400
	s_and_b32 s80, s11, 15
	s_lshr_b32 s81, s11, 4
	s_movk_i32 s78, 0x2000
	s_movk_i32 s79, 0x800
	s_mov_b32 s34, 0x10000
	s_lshl_b32 s31, s10, 23
	s_lshl_b32 s11, s80, 19
	s_add_u32 s31, s31, s11
	s_lshl_b32 s11, s81, 8
	s_add_u32 s31, s31, s11
	s_add_u32 s31, s6, s31
	s_addc_u32 s11, s7, 0
	s_bfe_u32 s78, s81, 0x30001
	s_lshl_b32 s78, s78, 8
	s_lshr_b32 s79, s81, 4
	s_lshl_b32 s79, s79, 7
	s_add_u32 s78, s78, s79
	s_and_b32 s79, s81, 1
	s_lshl_b32 s79, s79, 6
	s_add_u32 s78, s78, s79
	s_lshl_b32 s78, s78, 11
	s_lshl_b32 s79, s80, 7
	s_add_u32 s78, s78, s79
	s_lshl_b32 s79, s10, 22
	s_add_u32 s78, s78, s79
	s_add_u32 s81, s78, 0xae00000
	s_mov_b32 s80, s31
	s_mov_b32 s31, s81
	s_mov_b32 s81, s11
	s_movk_i32 s78, 0x2000
	s_movk_i32 s79, 0x800
	s_branch .Ltq2_dec1

.Ltq2_exit:
	s_waitcnt vmcnt(0)
	v_mov_b32_e32 v177, 0
	s_andn2_b64 vcc, exec, s[96:97]
	s_cbranch_vccnz .LBB0_823
	s_waitcnt vmcnt(0)
	v_mov_b32_e32 v0, v220
	s_barrier
	s_nop 0
	v_cmp_eq_u32_e32 vcc, 0, v0
	s_and_saveexec_b64 s[2:3], vcc
	s_cbranch_execz .LBB0_822
	v_readlane_b32 s4, v255, 6
	s_waitcnt vmcnt(0) expcnt(0) lgkmcnt(0)
	s_nop 0
	v_mov_b32_e32 v0, s4
	ds_read_b32 v2, v0
	ds_read_b32 v0, v0 offset:4
	s_waitcnt lgkmcnt(1)
	v_cmp_ne_u32_e32 vcc, 0, v2
	s_cbranch_vccnz .LBB0_790
	v_readlane_b32 s6, v255, 0
	v_readlane_b32 s7, v255, 1
	s_load_dwordx2 s[4:5], s[6:7], 0x4
	s_mov_b32 s10, 0
	s_waitcnt lgkmcnt(0)
	s_mul_i32 s9, s4, s13
	s_mul_i32 s9, s9, s5
	s_branch .LBB0_779
